# code placement: the three GEMM K-loop heads padded to a 256-byte boundary (all other code kept at its baseline byte phase)
# speedup vs baseline: 1.0056x; 1.0018x over previous
.LBB0_94:
	s_ashr_i32 s53, s52, 31
	s_lshl_b64 s[30:31], s[52:53], 19
	s_add_u32 s56, s28, s30
	s_addc_u32 s57, s29, s31
	s_and_b64 s[30:31], s[38:39], exec
	s_cselect_b32 s30, s57, s41
	s_cselect_b32 s31, s56, s40
	s_ashr_i32 s55, s54, 31
	s_lshl_b64 s[34:35], s[54:55], 19
	s_add_u32 s58, s0, s34
	s_addc_u32 s59, s1, s35
	s_and_b64 s[34:35], s[38:39], exec
	s_cselect_b32 s33, s59, s63
	s_cselect_b32 s34, s58, s62
	s_add_u32 s40, s40, 0x40080
	s_addc_u32 s41, s41, 0
	s_add_u32 s35, s62, 0x100
	v_mov_b32_e32 v0, 0
	s_addc_u32 s53, s63, 0
	s_mov_b32 s55, -2
	v_mov_b32_e32 v1, v0
	v_mov_b32_e32 v2, v0
	v_mov_b32_e32 v3, v0
	v_mov_b32_e32 v4, v0
	v_mov_b32_e32 v5, v0
	v_mov_b32_e32 v6, v0
	v_mov_b32_e32 v7, v0
	v_mov_b32_e32 v16, v0
	v_mov_b32_e32 v17, v0
	v_mov_b32_e32 v18, v0
	v_mov_b32_e32 v19, v0
	v_mov_b32_e32 v20, v0
	v_mov_b32_e32 v21, v0
	v_mov_b32_e32 v22, v0
	v_mov_b32_e32 v23, v0
	v_mov_b32_e32 v32, v0
	v_mov_b32_e32 v33, v0
	v_mov_b32_e32 v34, v0
	v_mov_b32_e32 v35, v0
	v_mov_b32_e32 v36, v0
	v_mov_b32_e32 v37, v0
	v_mov_b32_e32 v38, v0
	v_mov_b32_e32 v39, v0
	v_mov_b32_e32 v48, v0
	v_mov_b32_e32 v49, v0
	v_mov_b32_e32 v50, v0
	v_mov_b32_e32 v51, v0
	v_mov_b32_e32 v52, v0
	v_mov_b32_e32 v53, v0
	v_mov_b32_e32 v54, v0
	v_mov_b32_e32 v55, v0
	v_mov_b32_e32 v8, v0
	v_mov_b32_e32 v9, v0
	v_mov_b32_e32 v10, v0
	v_mov_b32_e32 v11, v0
	v_mov_b32_e32 v12, v0
	v_mov_b32_e32 v13, v0
	v_mov_b32_e32 v14, v0
	v_mov_b32_e32 v15, v0
	v_mov_b32_e32 v24, v0
	v_mov_b32_e32 v25, v0
	v_mov_b32_e32 v26, v0
	v_mov_b32_e32 v27, v0
	v_mov_b32_e32 v28, v0
	v_mov_b32_e32 v29, v0
	v_mov_b32_e32 v30, v0
	v_mov_b32_e32 v31, v0
	v_mov_b32_e32 v40, v0
	v_mov_b32_e32 v41, v0
	v_mov_b32_e32 v42, v0
	v_mov_b32_e32 v43, v0
	v_mov_b32_e32 v44, v0
	v_mov_b32_e32 v45, v0
	v_mov_b32_e32 v46, v0
	v_mov_b32_e32 v47, v0
	v_mov_b32_e32 v56, v0
	v_mov_b32_e32 v57, v0
	v_mov_b32_e32 v58, v0
	v_mov_b32_e32 v59, v0
	v_mov_b32_e32 v60, v0
	v_mov_b32_e32 v61, v0
	v_mov_b32_e32 v62, v0
	v_mov_b32_e32 v63, v0
	v_mov_b32_e32 v64, v0
	v_mov_b32_e32 v65, v0
	v_mov_b32_e32 v66, v0
	v_mov_b32_e32 v67, v0
	v_mov_b32_e32 v68, v0
	v_mov_b32_e32 v69, v0
	v_mov_b32_e32 v70, v0
	v_mov_b32_e32 v71, v0
	v_mov_b32_e32 v80, v0
	v_mov_b32_e32 v81, v0
	v_mov_b32_e32 v82, v0
	v_mov_b32_e32 v83, v0
	v_mov_b32_e32 v84, v0
	v_mov_b32_e32 v85, v0
	v_mov_b32_e32 v86, v0
	v_mov_b32_e32 v87, v0
	v_mov_b32_e32 v96, v0
	v_mov_b32_e32 v97, v0
	v_mov_b32_e32 v98, v0
	v_mov_b32_e32 v99, v0
	v_mov_b32_e32 v100, v0
	v_mov_b32_e32 v101, v0
	v_mov_b32_e32 v102, v0
	v_mov_b32_e32 v103, v0
	v_mov_b32_e32 v112, v0
	v_mov_b32_e32 v113, v0
	v_mov_b32_e32 v114, v0
	v_mov_b32_e32 v115, v0
	v_mov_b32_e32 v116, v0
	v_mov_b32_e32 v117, v0
	v_mov_b32_e32 v118, v0
	v_mov_b32_e32 v119, v0
	v_mov_b32_e32 v72, v0
	v_mov_b32_e32 v73, v0
	v_mov_b32_e32 v74, v0
	v_mov_b32_e32 v75, v0
	v_mov_b32_e32 v76, v0
	v_mov_b32_e32 v77, v0
	v_mov_b32_e32 v78, v0
	v_mov_b32_e32 v79, v0
	v_mov_b32_e32 v88, v0
	v_mov_b32_e32 v89, v0
	v_mov_b32_e32 v90, v0
	v_mov_b32_e32 v91, v0
	v_mov_b32_e32 v92, v0
	v_mov_b32_e32 v93, v0
	v_mov_b32_e32 v94, v0
	v_mov_b32_e32 v95, v0
	v_mov_b32_e32 v104, v0
	v_mov_b32_e32 v105, v0
	v_mov_b32_e32 v106, v0
	v_mov_b32_e32 v107, v0
	v_mov_b32_e32 v108, v0
	v_mov_b32_e32 v109, v0
	v_mov_b32_e32 v110, v0
	v_mov_b32_e32 v111, v0
	v_mov_b32_e32 v120, v0
	v_mov_b32_e32 v121, v0
	v_mov_b32_e32 v122, v0
	v_mov_b32_e32 v123, v0
	v_mov_b32_e32 v124, v0
	v_mov_b32_e32 v125, v0
	v_mov_b32_e32 v126, v0
	v_mov_b32_e32 v127, v0
	s_nop 0
	s_nop 0
	s_nop 0
	s_nop 0
	s_nop 0
	s_nop 0
	s_nop 0
	s_nop 0
	s_nop 0
	s_nop 0
	s_nop 0
	s_nop 0
	s_nop 0
	s_nop 0
	s_nop 0
	s_nop 0
	s_nop 0
	s_nop 0
	s_nop 0
	s_nop 0
	s_nop 0
	s_nop 0
	s_nop 0
	s_nop 0
	s_nop 0
	s_nop 0
	s_nop 0
	s_nop 0
	s_nop 0
	s_nop 0
	s_nop 0
	s_nop 0
	s_nop 0
	s_nop 0
	s_nop 0
	s_nop 0
	s_nop 0
	s_nop 0
	s_nop 0
	s_nop 0
	s_nop 0
	s_nop 0
	s_nop 0
	s_nop 0
	s_nop 0
	s_nop 0
	s_nop 0
	s_nop 0
	s_nop 0
	s_nop 0

.LBB0_416:
	s_or_b64 exec, exec, s[0:1]
	v_mul_f32_e32 v5, v17, v5
	v_fmac_f32_e32 v5, v16, v4
	v_mul_f32_e32 v4, v19, v7
	v_fmac_f32_e32 v4, v18, v6
	v_pk_mul_f32 v[6:7], v[18:19], v[2:3]
	v_pk_mul_f32 v[2:3], v[16:17], v[0:1]
	v_add_f32_e32 v4, v5, v4
	v_bfe_u32 v0, v2, 16, 1
	v_add3_u32 v1, v2, v0, s17
	v_bfe_u32 v2, v3, 16, 1
	v_add3_u32 v2, v3, v2, s17
	v_bfe_u32 v3, v6, 16, 1
	v_bfe_u32 v5, v7, 16, 1
	v_add3_u32 v3, v6, v3, s17
	v_add3_u32 v5, v7, v5, s17
	v_and_b32_e32 v0, 0xffff0000, v1
	v_and_b32_e32 v2, 0xffff0000, v2
	v_and_b32_e32 v6, 0xffff0000, v3
	v_and_b32_e32 v5, 0xffff0000, v5
	v_add_f32_e32 v0, v0, v2
	v_add_f32_e32 v6, v6, v5
	v_add_f32_e32 v6, v0, v6
	ds_bpermute_b32 v7, v37, v6
	ds_bpermute_b32 v16, v37, v4
	v_or_b32_sdwa v22, v22, v21 dst_sel:DWORD dst_unused:UNUSED_PAD src0_sel:DWORD src1_sel:WORD_1
	v_ashrrev_i32_e32 v21, 31, v20
	v_lshlrev_b64 v[18:19], 11, v[20:21]
	v_or_b32_sdwa v23, v25, v23 dst_sel:DWORD dst_unused:UNUSED_PAD src0_sel:DWORD src1_sel:WORD_1
	v_lshl_add_u64 v[18:19], v[28:29], 0, v[18:19]
	v_or_b32_e32 v0, 0x60, v30
	global_store_dwordx2 v[18:19], v[22:23], off
	s_and_saveexec_b64 s[0:1], s[40:41]
	s_cbranch_execz .LBB0_401
	s_waitcnt lgkmcnt(1)
	v_add_f32_e32 v18, v6, v7
	v_lshl_add_u32 v6, v0, 7, v14
	v_ashrrev_i32_e32 v7, 31, v6
	v_lshlrev_b64 v[6:7], 2, v[6:7]
	s_waitcnt lgkmcnt(0)
	v_add_f32_e32 v4, v4, v16
	v_lshl_add_u64 v[16:17], s[12:13], 0, v[6:7]
	v_lshl_add_u64 v[6:7], s[14:15], 0, v[6:7]
	global_store_dword v[16:17], v18, off
	global_store_dword v[6:7], v4, off
	s_branch .LBB0_401
	s_nop 0
	s_nop 0
	s_nop 0
	s_nop 0
	s_nop 0
	s_nop 0
	s_nop 0
	s_nop 0
	s_nop 0
	s_nop 0
	s_nop 0
	s_nop 0
	s_nop 0
	s_nop 0
	s_nop 0
	s_nop 0
	s_nop 0
	s_nop 0
	s_nop 0
	s_nop 0
	s_nop 0
	s_nop 0
	s_nop 0
	s_nop 0
	s_nop 0
	s_nop 0
	s_nop 0
	s_nop 0
	s_nop 0
	s_nop 0
	s_nop 0
	s_nop 0
	s_nop 0
	s_nop 0
	s_nop 0
	s_nop 0
	s_nop 0
	s_nop 0
	s_nop 0
	s_nop 0
	s_nop 0
	s_nop 0
	s_nop 0
	s_nop 0
	s_nop 0
	s_nop 0
	s_nop 0
	s_nop 0
	s_nop 0
	s_nop 0
	s_nop 0
	s_nop 0
	s_nop 0
	s_nop 0
	s_nop 0
	s_nop 0
	s_nop 0
	s_nop 0
	s_nop 0
	s_nop 0
	s_nop 0
	s_nop 0
	s_nop 0

.LBB0_579:
	s_ashr_i32 s47, s46, 31
	s_lshl_b64 s[30:31], s[46:47], 19
	s_add_u32 s50, s10, s30
	s_addc_u32 s51, s11, s31
	s_and_b64 s[30:31], s[40:41], exec
	s_cselect_b32 s17, s51, s59
	s_cselect_b32 s30, s50, s58
	s_ashr_i32 s49, s48, 31
	s_lshl_b64 s[34:35], s[48:49], 19
	s_add_u32 s52, s6, s34
	s_addc_u32 s53, s7, s35
	s_and_b64 s[34:35], s[40:41], exec
	s_cselect_b32 s31, s53, s61
	s_cselect_b32 s33, s52, s60
	s_add_u32 s58, s58, 0x40080
	s_addc_u32 s59, s59, 0
	s_add_u32 s34, s60, 0x100
	v_mov_b32_e32 v0, 0
	s_addc_u32 s35, s61, 0
	s_mov_b32 s47, -2
	v_mov_b32_e32 v1, v0
	s_waitcnt lgkmcnt(0)
	v_mov_b32_e32 v2, v0
	v_mov_b32_e32 v3, v0
	v_mov_b32_e32 v4, v0
	v_mov_b32_e32 v5, v0
	v_mov_b32_e32 v6, v0
	v_mov_b32_e32 v7, v0
	v_mov_b32_e32 v16, v0
	v_mov_b32_e32 v17, v0
	v_mov_b32_e32 v18, v0
	v_mov_b32_e32 v19, v0
	v_mov_b32_e32 v20, v0
	v_mov_b32_e32 v21, v0
	v_mov_b32_e32 v22, v0
	v_mov_b32_e32 v23, v0
	v_mov_b32_e32 v32, v0
	v_mov_b32_e32 v33, v0
	v_mov_b32_e32 v34, v0
	v_mov_b32_e32 v35, v0
	v_mov_b32_e32 v36, v0
	v_mov_b32_e32 v37, v0
	v_mov_b32_e32 v38, v0
	v_mov_b32_e32 v39, v0
	v_mov_b32_e32 v48, v0
	v_mov_b32_e32 v49, v0
	v_mov_b32_e32 v50, v0
	v_mov_b32_e32 v51, v0
	v_mov_b32_e32 v52, v0
	v_mov_b32_e32 v53, v0
	v_mov_b32_e32 v54, v0
	v_mov_b32_e32 v55, v0
	v_mov_b32_e32 v8, v0
	v_mov_b32_e32 v9, v0
	v_mov_b32_e32 v10, v0
	v_mov_b32_e32 v11, v0
	v_mov_b32_e32 v12, v0
	v_mov_b32_e32 v13, v0
	v_mov_b32_e32 v14, v0
	v_mov_b32_e32 v15, v0
	v_mov_b32_e32 v24, v0
	v_mov_b32_e32 v25, v0
	v_mov_b32_e32 v26, v0
	v_mov_b32_e32 v27, v0
	v_mov_b32_e32 v28, v0
	v_mov_b32_e32 v29, v0
	v_mov_b32_e32 v30, v0
	v_mov_b32_e32 v31, v0
	v_mov_b32_e32 v40, v0
	v_mov_b32_e32 v41, v0
	v_mov_b32_e32 v42, v0
	v_mov_b32_e32 v43, v0
	v_mov_b32_e32 v44, v0
	v_mov_b32_e32 v45, v0
	v_mov_b32_e32 v46, v0
	v_mov_b32_e32 v47, v0
	v_mov_b32_e32 v56, v0
	v_mov_b32_e32 v57, v0
	v_mov_b32_e32 v58, v0
	v_mov_b32_e32 v59, v0
	v_mov_b32_e32 v60, v0
	v_mov_b32_e32 v61, v0
	v_mov_b32_e32 v62, v0
	v_mov_b32_e32 v63, v0
	v_mov_b32_e32 v64, v0
	v_mov_b32_e32 v65, v0
	v_mov_b32_e32 v66, v0
	v_mov_b32_e32 v67, v0
	v_mov_b32_e32 v68, v0
	v_mov_b32_e32 v69, v0
	v_mov_b32_e32 v70, v0
	v_mov_b32_e32 v71, v0
	v_mov_b32_e32 v80, v0
	v_mov_b32_e32 v81, v0
	v_mov_b32_e32 v82, v0
	v_mov_b32_e32 v83, v0
	v_mov_b32_e32 v84, v0
	v_mov_b32_e32 v85, v0
	v_mov_b32_e32 v86, v0
	v_mov_b32_e32 v87, v0
	v_mov_b32_e32 v96, v0
	v_mov_b32_e32 v97, v0
	v_mov_b32_e32 v98, v0
	v_mov_b32_e32 v99, v0
	v_mov_b32_e32 v100, v0
	v_mov_b32_e32 v101, v0
	v_mov_b32_e32 v102, v0
	v_mov_b32_e32 v103, v0
	v_mov_b32_e32 v112, v0
	v_mov_b32_e32 v113, v0
	v_mov_b32_e32 v114, v0
	v_mov_b32_e32 v115, v0
	v_mov_b32_e32 v116, v0
	v_mov_b32_e32 v117, v0
	v_mov_b32_e32 v118, v0
	v_mov_b32_e32 v119, v0
	v_mov_b32_e32 v72, v0
	v_mov_b32_e32 v73, v0
	v_mov_b32_e32 v74, v0
	v_mov_b32_e32 v75, v0
	v_mov_b32_e32 v76, v0
	v_mov_b32_e32 v77, v0
	v_mov_b32_e32 v78, v0
	v_mov_b32_e32 v79, v0
	v_mov_b32_e32 v88, v0
	v_mov_b32_e32 v89, v0
	v_mov_b32_e32 v90, v0
	v_mov_b32_e32 v91, v0
	v_mov_b32_e32 v92, v0
	v_mov_b32_e32 v93, v0
	v_mov_b32_e32 v94, v0
	v_mov_b32_e32 v95, v0
	v_mov_b32_e32 v104, v0
	v_mov_b32_e32 v105, v0
	v_mov_b32_e32 v106, v0
	v_mov_b32_e32 v107, v0
	v_mov_b32_e32 v108, v0
	v_mov_b32_e32 v109, v0
	v_mov_b32_e32 v110, v0
	v_mov_b32_e32 v111, v0
	v_mov_b32_e32 v120, v0
	v_mov_b32_e32 v121, v0
	v_mov_b32_e32 v122, v0
	v_mov_b32_e32 v123, v0
	v_mov_b32_e32 v124, v0
	v_mov_b32_e32 v125, v0
	v_mov_b32_e32 v126, v0
	v_mov_b32_e32 v127, v0
	s_nop 0
	s_nop 0
	s_nop 0
	s_nop 0
	s_nop 0
	s_nop 0
	s_nop 0
	s_nop 0
	s_nop 0
	s_nop 0
	s_nop 0
	s_nop 0
	s_nop 0
	s_nop 0
	s_nop 0
	s_nop 0
	s_nop 0
	s_nop 0
	s_nop 0
	s_nop 0
	s_nop 0
	s_nop 0
	s_nop 0
	s_nop 0
	s_nop 0
	s_nop 0
	s_nop 0
	s_nop 0
	s_nop 0
	s_nop 0
	s_nop 0
	s_nop 0
	s_nop 0
	s_nop 0
	s_nop 0
	s_nop 0
	s_nop 0
	s_nop 0
	s_nop 0

.LBB0_599:
	s_or_b64 exec, exec, s[56:57]
	s_andn2_b64 vcc, exec, s[40:41]
	s_mov_b64 s[40:41], -1
	s_cbranch_vccnz .LBB0_572
	s_andn2_b64 vcc, exec, s[0:1]
	s_cbranch_vccnz .LBB0_571
	s_barrier
	s_branch .LBB0_571
	s_nop 0
	s_nop 0
	s_nop 0
	s_nop 0
	s_nop 0
	s_nop 0
	s_nop 0
	s_nop 0
	s_nop 0
	s_nop 0
	s_nop 0
	s_nop 0
	s_nop 0
	s_nop 0
	s_nop 0
	s_nop 0
	s_nop 0
	s_nop 0
	s_nop 0
	s_nop 0
	s_nop 0
	s_nop 0
	s_nop 0
	s_nop 0
	s_nop 0

.LBB0_763:
	s_ashr_i32 s43, s42, 31
	s_lshl_b64 s[30:31], s[42:43], 19
	s_add_u32 s46, s28, s30
	s_addc_u32 s47, s29, s31
	s_and_b64 s[30:31], s[40:41], exec
	s_cselect_b32 s30, s47, s53
	s_cselect_b32 s31, s46, s52
	s_ashr_i32 s45, s44, 31
	s_lshl_b64 s[34:35], s[44:45], 19
	s_add_u32 s48, s7, s34
	s_addc_u32 s49, s58, s35
	s_and_b64 s[34:35], s[40:41], exec
	s_cselect_b32 s33, s49, s55
	s_cselect_b32 s34, s48, s54
	s_add_u32 s52, s52, 0x40080
	s_addc_u32 s53, s53, 0
	s_add_u32 s35, s54, 0x100
	v_mov_b32_e32 v0, 0
	s_addc_u32 s43, s55, 0
	s_mov_b32 s45, -2
	v_mov_b32_e32 v1, v0
	v_mov_b32_e32 v2, v0
	v_mov_b32_e32 v3, v0
	v_mov_b32_e32 v4, v0
	v_mov_b32_e32 v5, v0
	v_mov_b32_e32 v6, v0
	v_mov_b32_e32 v7, v0
	v_mov_b32_e32 v16, v0
	v_mov_b32_e32 v17, v0
	v_mov_b32_e32 v18, v0
	v_mov_b32_e32 v19, v0
	v_mov_b32_e32 v20, v0
	v_mov_b32_e32 v21, v0
	v_mov_b32_e32 v22, v0
	v_mov_b32_e32 v23, v0
	v_mov_b32_e32 v32, v0
	v_mov_b32_e32 v33, v0
	v_mov_b32_e32 v34, v0
	v_mov_b32_e32 v35, v0
	v_mov_b32_e32 v36, v0
	v_mov_b32_e32 v37, v0
	v_mov_b32_e32 v38, v0
	v_mov_b32_e32 v39, v0
	v_mov_b32_e32 v48, v0
	v_mov_b32_e32 v49, v0
	v_mov_b32_e32 v50, v0
	v_mov_b32_e32 v51, v0
	v_mov_b32_e32 v52, v0
	v_mov_b32_e32 v53, v0
	v_mov_b32_e32 v54, v0
	v_mov_b32_e32 v55, v0
	v_mov_b32_e32 v8, v0
	v_mov_b32_e32 v9, v0
	v_mov_b32_e32 v10, v0
	v_mov_b32_e32 v11, v0
	v_mov_b32_e32 v12, v0
	v_mov_b32_e32 v13, v0
	v_mov_b32_e32 v14, v0
	v_mov_b32_e32 v15, v0
	v_mov_b32_e32 v24, v0
	v_mov_b32_e32 v25, v0
	v_mov_b32_e32 v26, v0
	v_mov_b32_e32 v27, v0
	v_mov_b32_e32 v28, v0
	v_mov_b32_e32 v29, v0
	v_mov_b32_e32 v30, v0
	v_mov_b32_e32 v31, v0
	v_mov_b32_e32 v40, v0
	v_mov_b32_e32 v41, v0
	v_mov_b32_e32 v42, v0
	v_mov_b32_e32 v43, v0
	v_mov_b32_e32 v44, v0
	v_mov_b32_e32 v45, v0
	v_mov_b32_e32 v46, v0
	v_mov_b32_e32 v47, v0
	v_mov_b32_e32 v56, v0
	v_mov_b32_e32 v57, v0
	v_mov_b32_e32 v58, v0
	v_mov_b32_e32 v59, v0
	v_mov_b32_e32 v60, v0
	v_mov_b32_e32 v61, v0
	v_mov_b32_e32 v62, v0
	v_mov_b32_e32 v63, v0
	v_mov_b32_e32 v96, v0
	v_mov_b32_e32 v97, v0
	v_mov_b32_e32 v98, v0
	v_mov_b32_e32 v99, v0
	v_mov_b32_e32 v100, v0
	v_mov_b32_e32 v101, v0
	v_mov_b32_e32 v102, v0
	v_mov_b32_e32 v103, v0
	v_mov_b32_e32 v112, v0
	v_mov_b32_e32 v113, v0
	v_mov_b32_e32 v114, v0
	v_mov_b32_e32 v115, v0
	v_mov_b32_e32 v116, v0
	v_mov_b32_e32 v117, v0
	v_mov_b32_e32 v118, v0
	v_mov_b32_e32 v119, v0
	v_mov_b32_e32 v128, v0
	v_mov_b32_e32 v129, v0
	v_mov_b32_e32 v130, v0
	v_mov_b32_e32 v131, v0
	v_mov_b32_e32 v132, v0
	v_mov_b32_e32 v133, v0
	v_mov_b32_e32 v134, v0
	v_mov_b32_e32 v135, v0
	v_mov_b32_e32 v144, v0
	v_mov_b32_e32 v145, v0
	v_mov_b32_e32 v146, v0
	v_mov_b32_e32 v147, v0
	v_mov_b32_e32 v148, v0
	v_mov_b32_e32 v149, v0
	v_mov_b32_e32 v150, v0
	v_mov_b32_e32 v151, v0
	v_mov_b32_e32 v104, v0
	v_mov_b32_e32 v105, v0
	v_mov_b32_e32 v106, v0
	v_mov_b32_e32 v107, v0
	v_mov_b32_e32 v108, v0
	v_mov_b32_e32 v109, v0
	v_mov_b32_e32 v110, v0
	v_mov_b32_e32 v111, v0
	v_mov_b32_e32 v120, v0
	v_mov_b32_e32 v121, v0
	v_mov_b32_e32 v122, v0
	v_mov_b32_e32 v123, v0
	v_mov_b32_e32 v124, v0
	v_mov_b32_e32 v125, v0
	v_mov_b32_e32 v126, v0
	v_mov_b32_e32 v127, v0
	v_mov_b32_e32 v136, v0
	v_mov_b32_e32 v137, v0
	v_mov_b32_e32 v138, v0
	v_mov_b32_e32 v139, v0
	v_mov_b32_e32 v140, v0
	v_mov_b32_e32 v141, v0
	v_mov_b32_e32 v142, v0
	v_mov_b32_e32 v143, v0
	v_mov_b32_e32 v152, v0
	v_mov_b32_e32 v153, v0
	v_mov_b32_e32 v154, v0
	v_mov_b32_e32 v155, v0
	v_mov_b32_e32 v156, v0
	v_mov_b32_e32 v157, v0
	v_mov_b32_e32 v158, v0
	v_mov_b32_e32 v159, v0
	s_nop 0
	s_nop 0
	s_nop 0
	s_nop 0
	s_nop 0
	s_nop 0
	s_nop 0
	s_nop 0
	s_nop 0
	s_nop 0
	s_nop 0
	s_nop 0
	s_nop 0
	s_nop 0
	s_nop 0
	s_nop 0
	s_nop 0
	s_nop 0
	s_nop 0
	s_nop 0
	s_nop 0
	s_nop 0
	s_nop 0
	s_nop 0
	s_nop 0
	s_nop 0
	s_nop 0
	s_nop 0
	s_nop 0
	s_nop 0
	s_nop 0
	s_nop 0

.LBB0_767:
	v_lshl_or_b32 v178, s17, 8, v182
	v_ashrrev_i32_e32 v179, 31, v178
	v_lshl_add_u32 v176, s50, 8, v180
	v_lshlrev_b64 v[64:65], 2, v[178:179]
	v_ashrrev_i32_e32 v177, 31, v176
	v_lshl_add_u64 v[66:67], s[12:13], 0, v[64:65]
	v_lshl_add_u64 v[72:73], s[10:11], 0, v[64:65]
	v_lshl_add_u64 v[188:189], v[176:177], 3, s[4:5]
	global_load_dwordx4 v[84:87], v[66:67], off offset:16
	global_load_dwordx4 v[92:95], v[66:67], off
	global_load_dwordx4 v[80:83], v[72:73], off offset:16
	global_load_dwordx4 v[88:91], v[72:73], off
	global_load_dwordx4 v[68:71], v[66:67], off offset:528
	global_load_dwordx4 v[76:79], v[66:67], off offset:512
	s_nop 0
	global_load_dwordx4 v[64:67], v[72:73], off offset:528
	s_nop 0
	global_load_dwordx4 v[72:75], v[72:73], off offset:512
	v_lshlrev_b64 v[186:187], 12, v[176:177]
	global_load_dwordx2 v[188:189], v[188:189], off
	v_lshl_add_u64 v[186:187], s[92:93], 0, v[186:187]
	v_lshlrev_b64 v[178:179], 1, v[178:179]
	v_lshl_add_u64 v[186:187], v[186:187], 0, v[178:179]
	v_readlane_b32 s68, v246, 58
	s_mov_b64 s[50:51], -1
	s_andn2_b64 vcc, exec, s[40:41]
	v_readlane_b32 s69, v246, 59
	s_waitcnt vmcnt(0)
	v_xor_b32_e32 v87, 0x80000000, v87
	v_xor_b32_e32 v95, 0x80000000, v95
	v_xor_b32_e32 v94, 0x80000000, v94
	v_xor_b32_e32 v86, 0x80000000, v86
	v_xor_b32_e32 v71, 0x80000000, v71
	v_xor_b32_e32 v79, 0x80000000, v79
	v_xor_b32_e32 v78, 0x80000000, v78
	v_xor_b32_e32 v70, 0x80000000, v70
	v_pk_fma_f32 v[156:157], v[92:93], v[188:189], v[156:157] op_sel_hi:[1,0,1] neg_lo:[1,0,0] neg_hi:[1,0,0]
	v_pk_fma_f32 v[158:159], v[94:95], v[188:189], v[158:159] op_sel_hi:[1,0,1]
	v_pk_fma_f32 v[152:153], v[84:85], v[188:189], v[152:153] op_sel_hi:[1,0,1] neg_lo:[1,0,0] neg_hi:[1,0,0]
	v_pk_fma_f32 v[154:155], v[86:87], v[188:189], v[154:155] op_sel_hi:[1,0,1]
	v_pk_fma_f32 v[158:159], v[188:189], v[158:159], v[90:91] op_sel:[1,0,0]
	v_pk_fma_f32 v[156:157], v[188:189], v[156:157], v[88:89] op_sel:[1,0,0]
	v_pk_fma_f32 v[190:191], v[188:189], v[154:155], v[82:83] op_sel:[1,0,0]
	v_pk_fma_f32 v[154:155], v[188:189], v[152:153], v[80:81] op_sel:[1,0,0]
	v_cvt_pk_f16_f32 v152, v156, v157
	v_cvt_pk_f16_f32 v153, v158, v159
	v_cvt_pk_f16_f32 v154, v154, v155
	v_cvt_pk_f16_f32 v155, v190, v191
	v_pk_fma_f32 v[148:149], v[76:77], v[188:189], v[148:149] op_sel_hi:[1,0,1] neg_lo:[1,0,0] neg_hi:[1,0,0]
	v_pk_fma_f32 v[150:151], v[78:79], v[188:189], v[150:151] op_sel_hi:[1,0,1]
	v_pk_fma_f32 v[144:145], v[68:69], v[188:189], v[144:145] op_sel_hi:[1,0,1] neg_lo:[1,0,0] neg_hi:[1,0,0]
	v_pk_fma_f32 v[146:147], v[70:71], v[188:189], v[146:147] op_sel_hi:[1,0,1]
	global_store_dwordx4 v[186:187], v[152:155], off
	v_pk_fma_f32 v[150:151], v[188:189], v[150:151], v[74:75] op_sel:[1,0,0]
	v_pk_fma_f32 v[148:149], v[188:189], v[148:149], v[72:73] op_sel:[1,0,0]
	v_pk_fma_f32 v[152:153], v[188:189], v[146:147], v[66:67] op_sel:[1,0,0]
	v_pk_fma_f32 v[146:147], v[188:189], v[144:145], v[64:65] op_sel:[1,0,0]
	v_cvt_pk_f16_f32 v144, v148, v149
	v_cvt_pk_f16_f32 v145, v150, v151
	v_cvt_pk_f16_f32 v146, v146, v147
	v_cvt_pk_f16_f32 v147, v152, v153
	global_store_dwordx4 v[186:187], v[144:147], off offset:256
	s_nop 1
	v_or_b32_e32 v144, 16, v176
	v_ashrrev_i32_e32 v145, 31, v144
	v_lshlrev_b64 v[146:147], 12, v[144:145]
	v_lshl_add_u64 v[144:145], v[144:145], 3, s[4:5]
	global_load_dwordx2 v[144:145], v[144:145], off
	v_lshl_add_u64 v[146:147], s[92:93], 0, v[146:147]
	v_lshl_add_u64 v[146:147], v[146:147], 0, v[178:179]
	s_waitcnt vmcnt(0)
	v_pk_fma_f32 v[140:141], v[92:93], v[144:145], v[140:141] op_sel_hi:[1,0,1] neg_lo:[1,0,0] neg_hi:[1,0,0]
	v_pk_fma_f32 v[142:143], v[94:95], v[144:145], v[142:143] op_sel_hi:[1,0,1]
	v_pk_fma_f32 v[136:137], v[84:85], v[144:145], v[136:137] op_sel_hi:[1,0,1] neg_lo:[1,0,0] neg_hi:[1,0,0]
	v_pk_fma_f32 v[138:139], v[86:87], v[144:145], v[138:139] op_sel_hi:[1,0,1]
	v_pk_fma_f32 v[142:143], v[144:145], v[142:143], v[90:91] op_sel:[1,0,0]
	v_pk_fma_f32 v[140:141], v[144:145], v[140:141], v[88:89] op_sel:[1,0,0]
	v_pk_fma_f32 v[148:149], v[144:145], v[138:139], v[82:83] op_sel:[1,0,0]
	v_pk_fma_f32 v[138:139], v[144:145], v[136:137], v[80:81] op_sel:[1,0,0]
	v_cvt_pk_f16_f32 v136, v140, v141
	v_cvt_pk_f16_f32 v137, v142, v143
	v_cvt_pk_f16_f32 v138, v138, v139
	v_cvt_pk_f16_f32 v139, v148, v149
	v_pk_fma_f32 v[132:133], v[76:77], v[144:145], v[132:133] op_sel_hi:[1,0,1] neg_lo:[1,0,0] neg_hi:[1,0,0]
	v_pk_fma_f32 v[134:135], v[78:79], v[144:145], v[134:135] op_sel_hi:[1,0,1]
	v_pk_fma_f32 v[128:129], v[68:69], v[144:145], v[128:129] op_sel_hi:[1,0,1] neg_lo:[1,0,0] neg_hi:[1,0,0]
	v_pk_fma_f32 v[130:131], v[70:71], v[144:145], v[130:131] op_sel_hi:[1,0,1]
	global_store_dwordx4 v[146:147], v[136:139], off
	v_pk_fma_f32 v[134:135], v[144:145], v[134:135], v[74:75] op_sel:[1,0,0]
	v_pk_fma_f32 v[132:133], v[144:145], v[132:133], v[72:73] op_sel:[1,0,0]
	v_pk_fma_f32 v[136:137], v[144:145], v[130:131], v[66:67] op_sel:[1,0,0]
	v_pk_fma_f32 v[130:131], v[144:145], v[128:129], v[64:65] op_sel:[1,0,0]
	v_cvt_pk_f16_f32 v128, v132, v133
	v_cvt_pk_f16_f32 v129, v134, v135
	v_cvt_pk_f16_f32 v130, v130, v131
	v_cvt_pk_f16_f32 v131, v136, v137
	global_store_dwordx4 v[146:147], v[128:131], off offset:256
	s_nop 1
	v_or_b32_e32 v128, 32, v176
	v_ashrrev_i32_e32 v129, 31, v128
	v_lshlrev_b64 v[130:131], 12, v[128:129]
	v_lshl_add_u64 v[128:129], v[128:129], 3, s[4:5]
	global_load_dwordx2 v[128:129], v[128:129], off
	v_lshl_add_u64 v[130:131], s[92:93], 0, v[130:131]
	v_lshl_add_u64 v[130:131], v[130:131], 0, v[178:179]
	s_waitcnt vmcnt(0)
	v_pk_fma_f32 v[124:125], v[92:93], v[128:129], v[124:125] op_sel_hi:[1,0,1] neg_lo:[1,0,0] neg_hi:[1,0,0]
	v_pk_fma_f32 v[126:127], v[94:95], v[128:129], v[126:127] op_sel_hi:[1,0,1]
	v_pk_fma_f32 v[120:121], v[84:85], v[128:129], v[120:121] op_sel_hi:[1,0,1] neg_lo:[1,0,0] neg_hi:[1,0,0]
	v_pk_fma_f32 v[122:123], v[86:87], v[128:129], v[122:123] op_sel_hi:[1,0,1]
	v_pk_fma_f32 v[126:127], v[128:129], v[126:127], v[90:91] op_sel:[1,0,0]
	v_pk_fma_f32 v[124:125], v[128:129], v[124:125], v[88:89] op_sel:[1,0,0]
	v_pk_fma_f32 v[132:133], v[128:129], v[122:123], v[82:83] op_sel:[1,0,0]
	v_pk_fma_f32 v[122:123], v[128:129], v[120:121], v[80:81] op_sel:[1,0,0]
	v_cvt_pk_f16_f32 v120, v124, v125
	v_cvt_pk_f16_f32 v121, v126, v127
	v_cvt_pk_f16_f32 v122, v122, v123
	v_cvt_pk_f16_f32 v123, v132, v133
	v_pk_fma_f32 v[116:117], v[76:77], v[128:129], v[116:117] op_sel_hi:[1,0,1] neg_lo:[1,0,0] neg_hi:[1,0,0]
	v_pk_fma_f32 v[118:119], v[78:79], v[128:129], v[118:119] op_sel_hi:[1,0,1]
	v_pk_fma_f32 v[112:113], v[68:69], v[128:129], v[112:113] op_sel_hi:[1,0,1] neg_lo:[1,0,0] neg_hi:[1,0,0]
	v_pk_fma_f32 v[114:115], v[70:71], v[128:129], v[114:115] op_sel_hi:[1,0,1]
	global_store_dwordx4 v[130:131], v[120:123], off
	v_pk_fma_f32 v[118:119], v[128:129], v[118:119], v[74:75] op_sel:[1,0,0]
	v_pk_fma_f32 v[116:117], v[128:129], v[116:117], v[72:73] op_sel:[1,0,0]
	v_pk_fma_f32 v[120:121], v[128:129], v[114:115], v[66:67] op_sel:[1,0,0]
	v_pk_fma_f32 v[114:115], v[128:129], v[112:113], v[64:65] op_sel:[1,0,0]
	v_cvt_pk_f16_f32 v112, v116, v117
	v_cvt_pk_f16_f32 v113, v118, v119
	v_cvt_pk_f16_f32 v114, v114, v115
	v_cvt_pk_f16_f32 v115, v120, v121
	global_store_dwordx4 v[130:131], v[112:115], off offset:256
	s_nop 1
	v_or_b32_e32 v112, 48, v176
	v_ashrrev_i32_e32 v113, 31, v112
	v_lshlrev_b64 v[114:115], 12, v[112:113]
	v_lshl_add_u64 v[112:113], v[112:113], 3, s[4:5]
	global_load_dwordx2 v[112:113], v[112:113], off
	v_lshl_add_u64 v[114:115], s[92:93], 0, v[114:115]
	v_lshl_add_u64 v[114:115], v[114:115], 0, v[178:179]
	s_waitcnt vmcnt(0)
	v_pk_fma_f32 v[108:109], v[92:93], v[112:113], v[108:109] op_sel_hi:[1,0,1] neg_lo:[1,0,0] neg_hi:[1,0,0]
	v_pk_fma_f32 v[110:111], v[94:95], v[112:113], v[110:111] op_sel_hi:[1,0,1]
	v_pk_fma_f32 v[104:105], v[84:85], v[112:113], v[104:105] op_sel_hi:[1,0,1] neg_lo:[1,0,0] neg_hi:[1,0,0]
	v_pk_fma_f32 v[106:107], v[86:87], v[112:113], v[106:107] op_sel_hi:[1,0,1]
	v_pk_fma_f32 v[110:111], v[112:113], v[110:111], v[90:91] op_sel:[1,0,0]
	v_pk_fma_f32 v[108:109], v[112:113], v[108:109], v[88:89] op_sel:[1,0,0]
	v_pk_fma_f32 v[116:117], v[112:113], v[106:107], v[82:83] op_sel:[1,0,0]
	v_pk_fma_f32 v[106:107], v[112:113], v[104:105], v[80:81] op_sel:[1,0,0]
	v_cvt_pk_f16_f32 v104, v108, v109
	v_cvt_pk_f16_f32 v105, v110, v111
	v_cvt_pk_f16_f32 v106, v106, v107
	v_cvt_pk_f16_f32 v107, v116, v117
	v_pk_fma_f32 v[100:101], v[76:77], v[112:113], v[100:101] op_sel_hi:[1,0,1] neg_lo:[1,0,0] neg_hi:[1,0,0]
	v_pk_fma_f32 v[102:103], v[78:79], v[112:113], v[102:103] op_sel_hi:[1,0,1]
	v_pk_fma_f32 v[96:97], v[68:69], v[112:113], v[96:97] op_sel_hi:[1,0,1] neg_lo:[1,0,0] neg_hi:[1,0,0]
	v_pk_fma_f32 v[98:99], v[70:71], v[112:113], v[98:99] op_sel_hi:[1,0,1]
	global_store_dwordx4 v[114:115], v[104:107], off
	v_pk_fma_f32 v[102:103], v[112:113], v[102:103], v[74:75] op_sel:[1,0,0]
	v_pk_fma_f32 v[100:101], v[112:113], v[100:101], v[72:73] op_sel:[1,0,0]
	v_pk_fma_f32 v[104:105], v[112:113], v[98:99], v[66:67] op_sel:[1,0,0]
	v_pk_fma_f32 v[98:99], v[112:113], v[96:97], v[64:65] op_sel:[1,0,0]
	v_cvt_pk_f16_f32 v96, v100, v101
	v_cvt_pk_f16_f32 v97, v102, v103
	v_cvt_pk_f16_f32 v98, v98, v99
	v_cvt_pk_f16_f32 v99, v104, v105
	global_store_dwordx4 v[114:115], v[96:99], off offset:256
	s_nop 1
	v_add_u32_e32 v96, 0x80, v176
	v_ashrrev_i32_e32 v97, 31, v96
	v_lshlrev_b64 v[98:99], 12, v[96:97]
	v_lshl_add_u64 v[96:97], v[96:97], 3, s[4:5]
	global_load_dwordx2 v[96:97], v[96:97], off
	v_lshl_add_u64 v[98:99], s[92:93], 0, v[98:99]
	v_lshl_add_u64 v[98:99], v[98:99], 0, v[178:179]
	s_waitcnt vmcnt(0)
	v_pk_fma_f32 v[60:61], v[92:93], v[96:97], v[60:61] op_sel_hi:[1,0,1] neg_lo:[1,0,0] neg_hi:[1,0,0]
	v_pk_fma_f32 v[62:63], v[94:95], v[96:97], v[62:63] op_sel_hi:[1,0,1]
	v_pk_fma_f32 v[56:57], v[84:85], v[96:97], v[56:57] op_sel_hi:[1,0,1] neg_lo:[1,0,0] neg_hi:[1,0,0]
	v_pk_fma_f32 v[58:59], v[86:87], v[96:97], v[58:59] op_sel_hi:[1,0,1]
	v_pk_fma_f32 v[62:63], v[96:97], v[62:63], v[90:91] op_sel:[1,0,0]
	v_pk_fma_f32 v[60:61], v[96:97], v[60:61], v[88:89] op_sel:[1,0,0]
	v_pk_fma_f32 v[100:101], v[96:97], v[58:59], v[82:83] op_sel:[1,0,0]
	v_pk_fma_f32 v[58:59], v[96:97], v[56:57], v[80:81] op_sel:[1,0,0]
	v_cvt_pk_f16_f32 v56, v60, v61
	v_cvt_pk_f16_f32 v57, v62, v63
	v_cvt_pk_f16_f32 v58, v58, v59
	v_cvt_pk_f16_f32 v59, v100, v101
	v_pk_fma_f32 v[52:53], v[76:77], v[96:97], v[52:53] op_sel_hi:[1,0,1] neg_lo:[1,0,0] neg_hi:[1,0,0]
	v_pk_fma_f32 v[54:55], v[78:79], v[96:97], v[54:55] op_sel_hi:[1,0,1]
	v_pk_fma_f32 v[48:49], v[68:69], v[96:97], v[48:49] op_sel_hi:[1,0,1] neg_lo:[1,0,0] neg_hi:[1,0,0]
	v_pk_fma_f32 v[50:51], v[70:71], v[96:97], v[50:51] op_sel_hi:[1,0,1]
	global_store_dwordx4 v[98:99], v[56:59], off
	v_pk_fma_f32 v[54:55], v[96:97], v[54:55], v[74:75] op_sel:[1,0,0]
	v_pk_fma_f32 v[52:53], v[96:97], v[52:53], v[72:73] op_sel:[1,0,0]
	v_pk_fma_f32 v[56:57], v[96:97], v[50:51], v[66:67] op_sel:[1,0,0]
	v_pk_fma_f32 v[50:51], v[96:97], v[48:49], v[64:65] op_sel:[1,0,0]
	v_cvt_pk_f16_f32 v48, v52, v53
	v_cvt_pk_f16_f32 v49, v54, v55
	v_cvt_pk_f16_f32 v50, v50, v51
	v_cvt_pk_f16_f32 v51, v56, v57
	global_store_dwordx4 v[98:99], v[48:51], off offset:256
	s_nop 1
	v_add_u32_e32 v48, 0x90, v176
	v_ashrrev_i32_e32 v49, 31, v48
	v_lshlrev_b64 v[50:51], 12, v[48:49]
	v_lshl_add_u64 v[48:49], v[48:49], 3, s[4:5]
	global_load_dwordx2 v[48:49], v[48:49], off
	v_lshl_add_u64 v[50:51], s[92:93], 0, v[50:51]
	v_lshl_add_u64 v[50:51], v[50:51], 0, v[178:179]
	s_waitcnt vmcnt(0)
	v_pk_fma_f32 v[44:45], v[92:93], v[48:49], v[44:45] op_sel_hi:[1,0,1] neg_lo:[1,0,0] neg_hi:[1,0,0]
	v_pk_fma_f32 v[46:47], v[94:95], v[48:49], v[46:47] op_sel_hi:[1,0,1]
	v_pk_fma_f32 v[40:41], v[84:85], v[48:49], v[40:41] op_sel_hi:[1,0,1] neg_lo:[1,0,0] neg_hi:[1,0,0]
	v_pk_fma_f32 v[42:43], v[86:87], v[48:49], v[42:43] op_sel_hi:[1,0,1]
	v_pk_fma_f32 v[46:47], v[48:49], v[46:47], v[90:91] op_sel:[1,0,0]
	v_pk_fma_f32 v[44:45], v[48:49], v[44:45], v[88:89] op_sel:[1,0,0]
	v_pk_fma_f32 v[52:53], v[48:49], v[42:43], v[82:83] op_sel:[1,0,0]
	v_pk_fma_f32 v[42:43], v[48:49], v[40:41], v[80:81] op_sel:[1,0,0]
	v_cvt_pk_f16_f32 v40, v44, v45
	v_cvt_pk_f16_f32 v41, v46, v47
	v_cvt_pk_f16_f32 v42, v42, v43
	v_cvt_pk_f16_f32 v43, v52, v53
	v_pk_fma_f32 v[36:37], v[76:77], v[48:49], v[36:37] op_sel_hi:[1,0,1] neg_lo:[1,0,0] neg_hi:[1,0,0]
	v_pk_fma_f32 v[38:39], v[78:79], v[48:49], v[38:39] op_sel_hi:[1,0,1]
	v_pk_fma_f32 v[32:33], v[68:69], v[48:49], v[32:33] op_sel_hi:[1,0,1] neg_lo:[1,0,0] neg_hi:[1,0,0]
	v_pk_fma_f32 v[34:35], v[70:71], v[48:49], v[34:35] op_sel_hi:[1,0,1]
	global_store_dwordx4 v[50:51], v[40:43], off
	v_pk_fma_f32 v[38:39], v[48:49], v[38:39], v[74:75] op_sel:[1,0,0]
	v_pk_fma_f32 v[36:37], v[48:49], v[36:37], v[72:73] op_sel:[1,0,0]
	v_pk_fma_f32 v[40:41], v[48:49], v[34:35], v[66:67] op_sel:[1,0,0]
	v_pk_fma_f32 v[34:35], v[48:49], v[32:33], v[64:65] op_sel:[1,0,0]
	v_cvt_pk_f16_f32 v32, v36, v37
	v_cvt_pk_f16_f32 v33, v38, v39
	v_cvt_pk_f16_f32 v34, v34, v35
	v_cvt_pk_f16_f32 v35, v40, v41
	global_store_dwordx4 v[50:51], v[32:35], off offset:256
	s_nop 1
	v_add_u32_e32 v32, 0xa0, v176
	v_ashrrev_i32_e32 v33, 31, v32
	v_lshlrev_b64 v[34:35], 12, v[32:33]
	v_lshl_add_u64 v[32:33], v[32:33], 3, s[4:5]
	global_load_dwordx2 v[32:33], v[32:33], off
	v_lshl_add_u64 v[34:35], s[92:93], 0, v[34:35]
	v_lshl_add_u64 v[34:35], v[34:35], 0, v[178:179]
	s_waitcnt vmcnt(0)
	v_pk_fma_f32 v[28:29], v[92:93], v[32:33], v[28:29] op_sel_hi:[1,0,1] neg_lo:[1,0,0] neg_hi:[1,0,0]
	v_pk_fma_f32 v[30:31], v[94:95], v[32:33], v[30:31] op_sel_hi:[1,0,1]
	v_pk_fma_f32 v[24:25], v[84:85], v[32:33], v[24:25] op_sel_hi:[1,0,1] neg_lo:[1,0,0] neg_hi:[1,0,0]
	v_pk_fma_f32 v[26:27], v[86:87], v[32:33], v[26:27] op_sel_hi:[1,0,1]
	v_pk_fma_f32 v[30:31], v[32:33], v[30:31], v[90:91] op_sel:[1,0,0]
	v_pk_fma_f32 v[28:29], v[32:33], v[28:29], v[88:89] op_sel:[1,0,0]
	v_pk_fma_f32 v[36:37], v[32:33], v[26:27], v[82:83] op_sel:[1,0,0]
	v_pk_fma_f32 v[26:27], v[32:33], v[24:25], v[80:81] op_sel:[1,0,0]
	v_cvt_pk_f16_f32 v24, v28, v29
	v_cvt_pk_f16_f32 v25, v30, v31
	v_cvt_pk_f16_f32 v26, v26, v27
	v_cvt_pk_f16_f32 v27, v36, v37
	v_pk_fma_f32 v[20:21], v[76:77], v[32:33], v[20:21] op_sel_hi:[1,0,1] neg_lo:[1,0,0] neg_hi:[1,0,0]
	v_pk_fma_f32 v[22:23], v[78:79], v[32:33], v[22:23] op_sel_hi:[1,0,1]
	v_pk_fma_f32 v[16:17], v[68:69], v[32:33], v[16:17] op_sel_hi:[1,0,1] neg_lo:[1,0,0] neg_hi:[1,0,0]
	v_pk_fma_f32 v[18:19], v[70:71], v[32:33], v[18:19] op_sel_hi:[1,0,1]
	global_store_dwordx4 v[34:35], v[24:27], off
	v_pk_fma_f32 v[22:23], v[32:33], v[22:23], v[74:75] op_sel:[1,0,0]
	v_pk_fma_f32 v[20:21], v[32:33], v[20:21], v[72:73] op_sel:[1,0,0]
	v_pk_fma_f32 v[24:25], v[32:33], v[18:19], v[66:67] op_sel:[1,0,0]
	v_pk_fma_f32 v[18:19], v[32:33], v[16:17], v[64:65] op_sel:[1,0,0]
	v_cvt_pk_f16_f32 v16, v20, v21
	v_cvt_pk_f16_f32 v17, v22, v23
	v_cvt_pk_f16_f32 v18, v18, v19
	v_cvt_pk_f16_f32 v19, v24, v25
	global_store_dwordx4 v[34:35], v[16:19], off offset:256
	s_nop 1
	v_add_u32_e32 v16, 0xb0, v176
	v_ashrrev_i32_e32 v17, 31, v16
	v_lshlrev_b64 v[18:19], 12, v[16:17]
	v_lshl_add_u64 v[16:17], v[16:17], 3, s[4:5]
	global_load_dwordx2 v[16:17], v[16:17], off
	v_lshl_add_u64 v[18:19], s[92:93], 0, v[18:19]
	v_lshl_add_u64 v[18:19], v[18:19], 0, v[178:179]
	s_waitcnt vmcnt(0)
	v_pk_fma_f32 v[12:13], v[92:93], v[16:17], v[12:13] op_sel_hi:[1,0,1] neg_lo:[1,0,0] neg_hi:[1,0,0]
	v_pk_fma_f32 v[14:15], v[94:95], v[16:17], v[14:15] op_sel_hi:[1,0,1]
	v_pk_fma_f32 v[8:9], v[84:85], v[16:17], v[8:9] op_sel_hi:[1,0,1] neg_lo:[1,0,0] neg_hi:[1,0,0]
	v_pk_fma_f32 v[10:11], v[86:87], v[16:17], v[10:11] op_sel_hi:[1,0,1]
	v_pk_fma_f32 v[14:15], v[16:17], v[14:15], v[90:91] op_sel:[1,0,0]
	v_pk_fma_f32 v[12:13], v[16:17], v[12:13], v[88:89] op_sel:[1,0,0]
	v_pk_fma_f32 v[20:21], v[16:17], v[10:11], v[82:83] op_sel:[1,0,0]
	v_pk_fma_f32 v[10:11], v[16:17], v[8:9], v[80:81] op_sel:[1,0,0]
	v_cvt_pk_f16_f32 v8, v12, v13
	v_cvt_pk_f16_f32 v9, v14, v15
	v_cvt_pk_f16_f32 v10, v10, v11
	v_cvt_pk_f16_f32 v11, v20, v21
	v_pk_fma_f32 v[4:5], v[76:77], v[16:17], v[4:5] op_sel_hi:[1,0,1] neg_lo:[1,0,0] neg_hi:[1,0,0]
	v_pk_fma_f32 v[6:7], v[78:79], v[16:17], v[6:7] op_sel_hi:[1,0,1]
	v_pk_fma_f32 v[0:1], v[68:69], v[16:17], v[0:1] op_sel_hi:[1,0,1] neg_lo:[1,0,0] neg_hi:[1,0,0]
	v_pk_fma_f32 v[2:3], v[70:71], v[16:17], v[2:3] op_sel_hi:[1,0,1]
	global_store_dwordx4 v[18:19], v[8:11], off
	v_pk_fma_f32 v[6:7], v[16:17], v[6:7], v[74:75] op_sel:[1,0,0]
	v_pk_fma_f32 v[4:5], v[16:17], v[4:5], v[72:73] op_sel:[1,0,0]
	v_pk_fma_f32 v[8:9], v[16:17], v[2:3], v[66:67] op_sel:[1,0,0]
	v_pk_fma_f32 v[2:3], v[16:17], v[0:1], v[64:65] op_sel:[1,0,0]
	v_cvt_pk_f16_f32 v0, v4, v5
	v_cvt_pk_f16_f32 v1, v6, v7
	v_cvt_pk_f16_f32 v2, v2, v3
	v_cvt_pk_f16_f32 v3, v8, v9
	global_store_dwordx4 v[18:19], v[0:3], off offset:256
	s_cbranch_vccnz .LBB0_756
	s_andn2_b64 vcc, exec, s[0:1]
	s_cbranch_vccnz .LBB0_755
	s_barrier
	s_branch .LBB0_755
	s_nop 0
	s_nop 0
	s_nop 0
	s_nop 0
	s_nop 0
	s_nop 0
	s_nop 0
	s_nop 0
	s_nop 0
	s_nop 0
	s_nop 0
	s_nop 0
	s_nop 0
	s_nop 0
	s_nop 0
	s_nop 0
	s_nop 0
	s_nop 0
	s_nop 0
	s_nop 0
	s_nop 0
	s_nop 0
	s_nop 0
	s_nop 0
	s_nop 0
	s_nop 0
	s_nop 0
	s_nop 0
	s_nop 0
	s_nop 0
	s_nop 0
	s_nop 0
